# conversion pre-run budgets L0:2 L1:1 L2:2 chunks per idle CU
# baseline (speedup 1.0000x reference)
.LBB0_710:
	s_waitcnt vmcnt(0)
	v_readlane_b32 s68, v253, 5
	s_barrier
	s_cmpk_lt_i32 s33, 206
	s_cbranch_scc1 .Lbrw_skip_L0
	s_and_b32 s100, s68, 0xffffffc0
	v_writelane_b32 v253, s100, 7
	s_lshl_b32 s100, s95, 6
	s_sub_i32 s100, 0, s100
	v_writelane_b32 v253, s100, 8
	s_nop 1
	v_readlane_b32 s100, v253, 7
	v_mbcnt_lo_u32_b32 v0, -1, 0
	v_mbcnt_hi_u32_b32 v0, -1, v0
	s_nop 1
	v_add_u32_e32 v0, s100, v0
	v_lshlrev_b32_e32 v0, 2, v0
	v_add_u32_e32 v0, 0x22400, v0
	v_writelane_b32 v255, s0, 0
	v_writelane_b32 v255, s1, 1
	v_writelane_b32 v255, s2, 2
	v_writelane_b32 v255, s3, 3
	v_writelane_b32 v255, s4, 4
	v_writelane_b32 v255, s5, 5
	v_writelane_b32 v255, s6, 6
	v_writelane_b32 v255, s7, 7
	v_writelane_b32 v255, s8, 8
	v_writelane_b32 v255, s9, 9
	v_writelane_b32 v255, s10, 10
	v_writelane_b32 v255, s11, 11
	v_writelane_b32 v255, s12, 12
	v_writelane_b32 v255, s13, 13
	v_writelane_b32 v255, s14, 14
	v_writelane_b32 v255, s15, 15
	v_writelane_b32 v255, s16, 16
	v_writelane_b32 v255, s17, 17
	v_writelane_b32 v255, s18, 18
	v_writelane_b32 v255, s19, 19
	v_writelane_b32 v255, s20, 20
	v_writelane_b32 v255, s21, 21
	v_writelane_b32 v255, s22, 22
	v_writelane_b32 v255, s23, 23
	v_writelane_b32 v255, s24, 24
	v_writelane_b32 v255, s25, 25
	v_writelane_b32 v255, s26, 26
	v_writelane_b32 v255, s27, 27
	v_writelane_b32 v255, s28, 28
	v_writelane_b32 v255, s29, 29
	v_writelane_b32 v255, s30, 30
	v_writelane_b32 v255, s31, 31
	v_writelane_b32 v255, s32, 32
	v_writelane_b32 v255, s33, 33
	v_writelane_b32 v255, s34, 34
	v_writelane_b32 v255, s35, 35
	v_writelane_b32 v255, s36, 36
	v_writelane_b32 v255, s37, 37
	v_writelane_b32 v255, s38, 38
	v_writelane_b32 v255, s39, 39
	v_writelane_b32 v255, s40, 40
	v_writelane_b32 v255, s41, 41
	v_writelane_b32 v255, s42, 42
	v_writelane_b32 v255, s43, 43
	v_writelane_b32 v255, s44, 44
	v_writelane_b32 v255, s45, 45
	v_writelane_b32 v255, s46, 46
	v_writelane_b32 v255, s47, 47
	v_writelane_b32 v255, s48, 48
	v_writelane_b32 v255, s49, 49
	v_writelane_b32 v255, s50, 50
	v_writelane_b32 v255, s51, 51
	v_writelane_b32 v255, s52, 52
	v_writelane_b32 v255, s53, 53
	v_writelane_b32 v255, s54, 54
	v_writelane_b32 v255, s55, 55
	v_writelane_b32 v255, s56, 56
	v_writelane_b32 v255, s57, 57
	v_writelane_b32 v255, s58, 58
	v_writelane_b32 v255, s59, 59
	v_writelane_b32 v255, s60, 60
	v_writelane_b32 v255, s61, 61
	v_writelane_b32 v255, s62, 62
	v_writelane_b32 v255, s63, 63
	ds_write_b32 v0, v255
	v_writelane_b32 v255, s64, 0
	v_writelane_b32 v255, s65, 1
	v_writelane_b32 v255, s66, 2
	v_writelane_b32 v255, s67, 3
	v_writelane_b32 v255, s68, 4
	v_writelane_b32 v255, s69, 5
	v_writelane_b32 v255, s70, 6
	v_writelane_b32 v255, s71, 7
	v_writelane_b32 v255, s72, 8
	v_writelane_b32 v255, s73, 9
	v_writelane_b32 v255, s74, 10
	v_writelane_b32 v255, s75, 11
	v_writelane_b32 v255, s76, 12
	v_writelane_b32 v255, s77, 13
	v_writelane_b32 v255, s78, 14
	v_writelane_b32 v255, s79, 15
	v_writelane_b32 v255, s80, 16
	v_writelane_b32 v255, s81, 17
	v_writelane_b32 v255, s82, 18
	v_writelane_b32 v255, s83, 19
	v_writelane_b32 v255, s84, 20
	v_writelane_b32 v255, s85, 21
	v_writelane_b32 v255, s86, 22
	v_writelane_b32 v255, s87, 23
	v_writelane_b32 v255, s88, 24
	v_writelane_b32 v255, s89, 25
	v_writelane_b32 v255, s90, 26
	v_writelane_b32 v255, s91, 27
	v_writelane_b32 v255, s92, 28
	v_writelane_b32 v255, s93, 29
	v_writelane_b32 v255, s94, 30
	v_writelane_b32 v255, s95, 31
	v_writelane_b32 v255, s96, 32
	v_writelane_b32 v255, s97, 33
	v_writelane_b32 v255, vcc_lo, 34
	v_writelane_b32 v255, vcc_hi, 35
	ds_write_b32 v0, v255 offset:2048
	s_waitcnt lgkmcnt(0)
	v_mov_b32_e32 v145, 0
	s_add_i32 s79, 0, 0x22040
	s_movk_i32 s80, 0x3000
	s_movk_i32 s81, 0xfff
	s_movk_i32 s82, 0x13ff
	s_movk_i32 s83, 0x23ff
	s_movk_i32 s84, 0x25ff
	s_add_i32 s85, 0, 0x22198
	s_add_i32 s86, 0, 0x22158
	s_add_i32 s87, 0, 0x22178
	s_add_i32 s88, 0, 0x221d8
	s_add_i32 s89, 0, 0x22160
	s_add_i32 s90, 0, 0x221a0
	s_add_i32 s91, 0, 0x221e0
	v_mov_b32_e32 v1, 0x221f0
	ds_read_b64 v[2:3], v1
	s_waitcnt lgkmcnt(0)
	v_readfirstlane_b32 s46, v2
	v_readfirstlane_b32 s47, v3
	s_mov_b32 s100, 2
	s_mov_b32 m0, 0x7fffffff
	s_branch .Lconv_entry_L0

.LBB0_3773:
	s_waitcnt vmcnt(0)
	s_barrier
	s_cmpk_lt_i32 s33, 206
	s_cbranch_scc1 .Lbrw_skip_L2
	v_readlane_b32 s100, v253, 7
	v_mbcnt_lo_u32_b32 v0, -1, 0
	v_mbcnt_hi_u32_b32 v0, -1, v0
	s_nop 1
	v_add_u32_e32 v0, s100, v0
	v_lshlrev_b32_e32 v0, 2, v0
	v_add_u32_e32 v0, 0x22400, v0
	v_writelane_b32 v255, s0, 0
	v_writelane_b32 v255, s1, 1
	v_writelane_b32 v255, s2, 2
	v_writelane_b32 v255, s3, 3
	v_writelane_b32 v255, s4, 4
	v_writelane_b32 v255, s5, 5
	v_writelane_b32 v255, s6, 6
	v_writelane_b32 v255, s7, 7
	v_writelane_b32 v255, s8, 8
	v_writelane_b32 v255, s9, 9
	v_writelane_b32 v255, s10, 10
	v_writelane_b32 v255, s11, 11
	v_writelane_b32 v255, s12, 12
	v_writelane_b32 v255, s13, 13
	v_writelane_b32 v255, s14, 14
	v_writelane_b32 v255, s15, 15
	v_writelane_b32 v255, s16, 16
	v_writelane_b32 v255, s17, 17
	v_writelane_b32 v255, s18, 18
	v_writelane_b32 v255, s19, 19
	v_writelane_b32 v255, s20, 20
	v_writelane_b32 v255, s21, 21
	v_writelane_b32 v255, s22, 22
	v_writelane_b32 v255, s23, 23
	v_writelane_b32 v255, s24, 24
	v_writelane_b32 v255, s25, 25
	v_writelane_b32 v255, s26, 26
	v_writelane_b32 v255, s27, 27
	v_writelane_b32 v255, s28, 28
	v_writelane_b32 v255, s29, 29
	v_writelane_b32 v255, s30, 30
	v_writelane_b32 v255, s31, 31
	v_writelane_b32 v255, s32, 32
	v_writelane_b32 v255, s33, 33
	v_writelane_b32 v255, s34, 34
	v_writelane_b32 v255, s35, 35
	v_writelane_b32 v255, s36, 36
	v_writelane_b32 v255, s37, 37
	v_writelane_b32 v255, s38, 38
	v_writelane_b32 v255, s39, 39
	v_writelane_b32 v255, s40, 40
	v_writelane_b32 v255, s41, 41
	v_writelane_b32 v255, s42, 42
	v_writelane_b32 v255, s43, 43
	v_writelane_b32 v255, s44, 44
	v_writelane_b32 v255, s45, 45
	v_writelane_b32 v255, s46, 46
	v_writelane_b32 v255, s47, 47
	v_writelane_b32 v255, s48, 48
	v_writelane_b32 v255, s49, 49
	v_writelane_b32 v255, s50, 50
	v_writelane_b32 v255, s51, 51
	v_writelane_b32 v255, s52, 52
	v_writelane_b32 v255, s53, 53
	v_writelane_b32 v255, s54, 54
	v_writelane_b32 v255, s55, 55
	v_writelane_b32 v255, s56, 56
	v_writelane_b32 v255, s57, 57
	v_writelane_b32 v255, s58, 58
	v_writelane_b32 v255, s59, 59
	v_writelane_b32 v255, s60, 60
	v_writelane_b32 v255, s61, 61
	v_writelane_b32 v255, s62, 62
	v_writelane_b32 v255, s63, 63
	ds_write_b32 v0, v255
	v_writelane_b32 v255, s64, 0
	v_writelane_b32 v255, s65, 1
	v_writelane_b32 v255, s66, 2
	v_writelane_b32 v255, s67, 3
	v_writelane_b32 v255, s68, 4
	v_writelane_b32 v255, s69, 5
	v_writelane_b32 v255, s70, 6
	v_writelane_b32 v255, s71, 7
	v_writelane_b32 v255, s72, 8
	v_writelane_b32 v255, s73, 9
	v_writelane_b32 v255, s74, 10
	v_writelane_b32 v255, s75, 11
	v_writelane_b32 v255, s76, 12
	v_writelane_b32 v255, s77, 13
	v_writelane_b32 v255, s78, 14
	v_writelane_b32 v255, s79, 15
	v_writelane_b32 v255, s80, 16
	v_writelane_b32 v255, s81, 17
	v_writelane_b32 v255, s82, 18
	v_writelane_b32 v255, s83, 19
	v_writelane_b32 v255, s84, 20
	v_writelane_b32 v255, s85, 21
	v_writelane_b32 v255, s86, 22
	v_writelane_b32 v255, s87, 23
	v_writelane_b32 v255, s88, 24
	v_writelane_b32 v255, s89, 25
	v_writelane_b32 v255, s90, 26
	v_writelane_b32 v255, s91, 27
	v_writelane_b32 v255, s92, 28
	v_writelane_b32 v255, s93, 29
	v_writelane_b32 v255, s94, 30
	v_writelane_b32 v255, s95, 31
	v_writelane_b32 v255, s96, 32
	v_writelane_b32 v255, s97, 33
	v_writelane_b32 v255, vcc_lo, 34
	v_writelane_b32 v255, vcc_hi, 35
	ds_write_b32 v0, v255 offset:2048
	s_waitcnt lgkmcnt(0)
	v_mov_b32_e32 v145, 0
	s_add_i32 s76, 0, 0x22040
	s_movk_i32 s77, 0x3080
	s_movk_i32 s78, 0xfff
	s_movk_i32 s79, 0x13ff
	s_movk_i32 s80, 0x23ff
	s_movk_i32 s81, 0x25ff
	s_add_i32 s82, 0, 0x22180
	s_add_i32 s83, 0, 0x22158
	s_add_i32 s84, 0, 0x22178
	s_add_i32 s85, 0, 0x221d8
	s_add_i32 s86, 0, 0x22160
	s_add_i32 s87, 0, 0x22190
	s_add_i32 s88, 0, 0x221e0
	s_movk_i32 s89, 0x11ff
	s_movk_i32 s90, 0x120f
	s_movk_i32 s91, 0x120b
	v_mov_b32_e32 v1, 0x221f0
	ds_read_b64 v[2:3], v1
	s_waitcnt lgkmcnt(0)
	v_readfirstlane_b32 s44, v2
	v_readfirstlane_b32 s45, v3
	s_mov_b32 s100, 2
	s_mov_b32 m0, 0x7fffffff
	s_branch .Ltramp_fwd_L2
